# v62 plus K/V tile loads issued right after the staging writes that free their registers (one step earlier)
# baseline (speedup 1.0000x reference)
.LBB0_308:
	v_sub_f32_e32 v0, v160, v215
	v_exp_f32_e32 v0, v0
	v_sub_f32_e32 v160, v161, v215
	v_exp_f32_e32 v160, v160
	v_sub_f32_e32 v161, v162, v215
	v_exp_f32_e32 v161, v161
	v_sub_f32_e32 v162, v163, v215
	v_exp_f32_e32 v162, v162
	v_sub_f32_e32 v164, v164, v215
	v_add_f32_e32 v163, v207, v0
	v_exp_f32_e32 v164, v164
	v_add_f32_e32 v163, v160, v163
	v_add_f32_e32 v163, v161, v163
	v_sub_f32_e32 v165, v165, v215
	v_add_f32_e32 v163, v162, v163
	v_exp_f32_e32 v165, v165
	v_sub_f32_e32 v166, v166, v215
	v_exp_f32_e32 v166, v166
	v_sub_f32_e32 v167, v167, v215
	v_add_f32_e32 v163, v164, v163
	v_exp_f32_e32 v167, v167
	v_cvt_pk_bf16_f32 v160, v0, v160
	v_cvt_pk_bf16_f32 v161, v161, v162
	v_add_f32_e32 v163, v165, v163
	v_cvt_pk_bf16_f32 v162, v164, v165
	v_add_f32_e32 v163, v166, v163
	v_add_f32_e32 v175, v167, v163
	v_cvt_pk_bf16_f32 v163, v166, v167
	s_nop 0
	s_waitcnt lgkmcnt(3)
	v_mfma_f32_32x32x16_bf16 v[128:143], v[148:151], v[160:163], v[128:143]
	ds_read_b128 v[148:151], v174 offset:27648
	v_sub_f32_e32 v164, v169, v215
	v_sub_f32_e32 v0, v168, v215
	v_exp_f32_e32 v168, v164
	s_waitcnt lgkmcnt(3)
	v_mfma_f32_32x32x16_bf16 v[112:127], v[144:147], v[160:163], v[112:127]
	ds_read_b128 v[144:147], v174 offset:30208
	v_sub_f32_e32 v164, v170, v215
	v_exp_f32_e32 v169, v164
	v_sub_f32_e32 v165, v171, v215
	s_waitcnt lgkmcnt(3)
	v_mfma_f32_32x32x16_bf16 v[96:111], v[156:159], v[160:163], v[96:111]
	ds_read_b128 v[156:159], v174 offset:32768
	v_exp_f32_e32 v170, v165
	v_sub_f32_e32 v164, v172, v215
	v_exp_f32_e32 v171, v164
	s_waitcnt lgkmcnt(3)
	v_mfma_f32_32x32x16_bf16 v[80:95], v[152:155], v[160:163], v[80:95]
	ds_read_b128 v[152:155], v174 offset:35328
	v_sub_f32_e32 v164, v173, v215
	v_sub_f32_e32 v14, v14, v215
	v_sub_f32_e32 v15, v15, v215
	s_waitcnt lgkmcnt(3)
	v_mfma_f32_32x32x16_bf16 v[64:79], v[148:151], v[160:163], v[64:79]
	ds_read_b128 v[148:151], v174 offset:17440
	v_exp_f32_e32 v0, v0
	v_exp_f32_e32 v172, v164
	s_waitcnt lgkmcnt(3)
	v_mfma_f32_32x32x16_bf16 v[48:63], v[144:147], v[160:163], v[48:63]
	ds_read_b128 v[144:147], v174 offset:20000
	v_exp_f32_e32 v14, v14
	v_exp_f32_e32 v15, v15
	s_waitcnt lgkmcnt(3)
	v_mfma_f32_32x32x16_bf16 v[32:47], v[156:159], v[160:163], v[32:47]
	ds_read_b128 v[156:159], v174 offset:22560
	v_cvt_pk_bf16_f32 v164, v0, v168
	v_cvt_pk_bf16_f32 v165, v169, v170
	s_waitcnt lgkmcnt(3)
	v_mfma_f32_32x32x16_bf16 v[16:31], v[152:155], v[160:163], v[16:31]
	ds_read_b128 v[152:155], v174 offset:25120
	v_cvt_pk_bf16_f32 v166, v171, v172
	v_cvt_pk_bf16_f32 v167, v14, v15
	s_nop 1
	s_waitcnt lgkmcnt(3)
	v_mfma_f32_32x32x16_bf16 v[128:143], v[148:151], v[164:167], v[128:143]
	ds_read_b128 v[148:151], v174 offset:27680
	s_waitcnt lgkmcnt(3)
	v_mfma_f32_32x32x16_bf16 v[112:127], v[144:147], v[164:167], v[112:127]
	ds_read_b128 v[144:147], v174 offset:30240
	v_subrev_u32_e32 v250, s73, v213
	s_waitcnt vmcnt(2)
	ds_write_b128 v250, v[2:5] offset:37888
	ds_write_b128 v250, v[6:9] offset:46592
	s_sub_i32 vcc_lo, s79, s77
	s_cmp_gt_u32 vcc_lo, 1
	s_cbranch_scc0 .Lat_nok
	v_lshl_add_u64 v[2:3], s[30:31], 0, v[190:191]
	s_nop 0
	v_add_co_u32_e32 v6, vcc, 0x13501000, v2
	s_nop 1
	v_addc_co_u32_e32 v7, vcc, 0, v3, vcc
	global_load_dwordx4 v[2:5], v[6:7], off
	s_nop 0
	global_load_dwordx4 v[6:9], v[6:7], off offset:256
.Lat_nok:
	s_waitcnt lgkmcnt(5)
	v_mfma_f32_32x32x16_bf16 v[96:111], v[156:159], v[164:167], v[96:111]
	ds_read_b128 v[156:159], v174 offset:32800
	s_waitcnt lgkmcnt(5)
	v_mfma_f32_32x32x16_bf16 v[80:95], v[152:155], v[164:167], v[80:95]
	ds_read_b128 v[152:155], v174 offset:35360
	s_waitcnt lgkmcnt(5)
	v_mfma_f32_32x32x16_bf16 v[64:79], v[148:151], v[164:167], v[64:79]
	s_waitcnt lgkmcnt(4)
	v_mfma_f32_32x32x16_bf16 v[48:63], v[144:147], v[164:167], v[48:63]
	v_subrev_u32_e32 v250, s73, v214
	v_add_u32_e32 v216, 0xd800, v250
	v_add_u32_e32 v250, 0x10000, v250
	s_sub_i32 vcc_lo, s79, s77
	s_cmp_gt_u32 vcc_lo, 1
	s_cbranch_scc0 .Lat_vlast
	s_waitcnt vmcnt(2)
	ds_write2_b64 v216, v[10:11], v[12:13] offset1:2
	ds_write2_b64 v250, v[176:177], v[178:179] offset1:2
	v_lshl_add_u64 v[10:11], s[30:31], 0, v[188:189]
	s_nop 0
	v_add_co_u32_e32 v12, vcc, 0x1f400000, v10
	s_nop 1
	v_addc_co_u32_e32 v13, vcc, 0, v11, vcc
	v_add_co_u32_e32 v176, vcc, 0x1f480000, v10
	s_nop 1
	v_addc_co_u32_e32 v177, vcc, 0, v11, vcc
	global_load_dwordx4 v[10:13], v[12:13], off offset:128
	s_nop 0
	global_load_dwordx4 v[176:179], v[176:177], off offset:128
	s_branch .Lat_vdone

.Lat_vdone:
	s_waitcnt lgkmcnt(3)
	v_mfma_f32_32x32x16_bf16 v[32:47], v[156:159], v[164:167], v[32:47]
	s_waitcnt lgkmcnt(2)
	v_mfma_f32_32x32x16_bf16 v[16:31], v[152:155], v[164:167], v[16:31]
	v_add_f32_e32 v0, v0, v175
	v_add_f32_e32 v0, v168, v0
	v_add_f32_e32 v0, v169, v0
	v_add_f32_e32 v0, v170, v0
	v_add_f32_e32 v0, v171, v0
	v_add_f32_e32 v0, v172, v0
	v_add_f32_e32 v0, v14, v0
	v_add_f32_e32 v207, v15, v0
	s_add_i32 s77, s77, 1
	v_lshl_add_u64 v[188:189], v[188:189], 0, 64
	s_mov_b64 vcc, 0x80000
	s_cmp_eq_u32 s79, s77
	v_lshl_add_u64 v[190:191], v[190:191], 0, vcc
	s_branch .Lat_step_end

.Lat_nostag:
	s_bitcmp1_b32 s77, 0
	s_cselect_b32 s73, 0x9400, 0
	s_cmp_gt_u32 s77, s49
	s_cbranch_scc1 .LBB0_309
	s_add_i32 vcc_lo, s73, 0
	s_add_i32 vcc_hi, vcc_lo, s78
	v_add3_u32 v0, vcc_hi, v211, v209
	v_add_u32_e32 v14, v210, v209
	ds_read_b128 v[144:147], v0
	ds_read_b128 v[160:163], v0 offset:32
	ds_read_b128 v[148:151], v14
	ds_read_b128 v[164:167], v14 offset:32
	ds_read_b128 v[216:219], v0 offset:64
	ds_read_b128 v[220:223], v0 offset:96
	ds_read_b128 v[224:227], v14 offset:64
	ds_read_b128 v[228:231], v14 offset:96
	v_add_u32_e32 v250, vcc_lo, v212
	s_waitcnt lgkmcnt(5)
	v_mfma_f32_32x32x16_bf16 v[144:159], v[144:147], v[148:151], 0
	s_waitcnt lgkmcnt(4)
	v_mfma_f32_32x32x16_bf16 v[160:175], v[160:163], v[164:167], 0
	s_waitcnt lgkmcnt(1)
	v_mfma_f32_32x32x16_bf16 v[144:159], v[216:219], v[224:227], v[144:159]
	ds_read_b128 v[216:219], v0 offset:128
	ds_read_b128 v[224:227], v0 offset:160
	ds_read_b128 v[232:235], v14 offset:128
	ds_read_b128 v[236:239], v14 offset:160
	ds_read_b128 v[240:243], v0 offset:192
	ds_read_b128 v[244:247], v0 offset:224
	ds_read_b128 v[180:183], v14 offset:192
	ds_read_b128 v[184:187], v14 offset:224
	s_waitcnt lgkmcnt(8)
	v_mfma_f32_32x32x16_bf16 v[160:175], v[220:223], v[228:231], v[160:175]
	s_waitcnt lgkmcnt(5)
	v_mfma_f32_32x32x16_bf16 v[144:159], v[216:219], v[232:235], v[144:159]
	s_waitcnt lgkmcnt(4)
	v_mfma_f32_32x32x16_bf16 v[160:175], v[224:227], v[236:239], v[160:175]
	s_waitcnt lgkmcnt(1)
	v_mfma_f32_32x32x16_bf16 v[144:159], v[240:243], v[180:183], v[144:159]
	s_waitcnt lgkmcnt(0)
	v_mfma_f32_32x32x16_bf16 v[160:175], v[244:247], v[184:187], v[160:175]
	s_nop 11
	v_pk_add_f32 v[14:15], v[158:159], v[174:175]
	v_add_u32_e32 v174, v250, v208
	v_pk_add_f32 v[166:167], v[150:151], v[166:167]
	v_pk_add_f32 v[164:165], v[148:149], v[164:165]
	v_pk_add_f32 v[162:163], v[146:147], v[162:163]
	v_pk_add_f32 v[160:161], v[144:145], v[160:161]
	ds_read_b128 v[148:151], v174 offset:17408
	ds_read_b128 v[144:147], v174 offset:19968
	v_pk_add_f32 v[172:173], v[156:157], v[172:173]
	v_pk_add_f32 v[170:171], v[154:155], v[170:171]
	v_pk_add_f32 v[168:169], v[152:153], v[168:169]
	ds_read_b128 v[156:159], v174 offset:22528
	ds_read_b128 v[152:155], v174 offset:25088
	s_cmp_lg_u32 s49, s77
	s_cbranch_scc1 .LBB0_313
	v_cndmask_b32_e64 v0, v160, v202, s[90:91]
	v_cndmask_b32_e64 v161, v202, v161, s[88:89]
	v_cndmask_b32_e64 v160, v0, v160, s[88:89]
	v_cndmask_b32_e64 v162, v162, v202, s[92:93]
	v_cndmask_b32_e64 v163, v163, v202, s[94:95]
	v_cndmask_b32_e64 v164, v164, v202, s[96:97]
	v_cndmask_b32_e64 v165, v165, v202, s[4:5]
	v_cndmask_b32_e64 v166, v166, v202, s[6:7]
	v_cndmask_b32_e64 v167, v167, v202, s[8:9]
	v_cndmask_b32_e64 v168, v168, v202, s[10:11]
	v_cndmask_b32_e64 v169, v169, v202, s[12:13]
	v_cndmask_b32_e64 v170, v170, v202, s[14:15]
	v_cndmask_b32_e64 v171, v171, v202, s[16:17]
	v_cndmask_b32_e64 v172, v172, v202, s[18:19]
	v_cndmask_b32_e64 v173, v173, v202, s[20:21]
	v_cndmask_b32_e64 v14, v14, v202, s[22:23]
	v_cndmask_b32_e64 v15, v15, v202, s[24:25]
